# cache-policy lever: nt on the once-read f32 input streams (x rows in P0, p/cache conversion loads, f32 weight loads of the pipelined transposes), on top of the de-serialised transposes
# speedup vs baseline: 1.0151x; 1.0097x over previous
; #define LAS __attribute__((address_space(3)))
; template <bool GU>
; __device__ __forceinline__ void transpose_item(const float* W, int K, int N, bf16* WT, const float* gs, LAS float* scr, int item, int lane) {
;     const int nblk = N / 32, kb = item / nblk, nb = item % nblk, k0 = 64 * kb, n0 = 32 * nb;
; #pragma unroll 16
;     for (int i = 0; i < 32; ++i) { const int kk = 2 * i + (lane >> 5); float w = W[(size_t)(k0 + kk) * N + n0 + (lane & 31)]; if (gs) w *= gs[k0 + kk]; scr[kk * 33 + (lane & 31)] = w; }
; __device__ __forceinline__ void conv_weights(LAS unsigned char* lds, unsigned char* ws, const PIn& I, const int l, const int wave, const int lane, const int gw, const int NGW, const int r_lo, const int r_hi) {
;     ...
;         if (r < I_IN) { transpose_item<false>(I.w_in + (size_t)l * DM * NIN, DM, NIN, (bf16*)(wb + W_IN), I.g_mix + l * DM, scr, r, lane); continue; } r -= I_IN;
.LBB0_19:
	s_mul_hi_i32 s4, s3, 0x38e38e39
	s_lshr_b32 s5, s4, 31
	s_ashr_i32 s4, s4, 4
	s_add_i32 s4, s4, s5
	s_mul_i32 s5, s4, 0x48
	s_sub_i32 s5, s3, s5
	s_lshl_b32 s12, s5, 5
	s_lshl_b32 s14, s4, 6
	s_ashr_i32 s13, s12, 31
	s_lshl_b64 s[4:5], s[12:13], 2
	v_add_u32_e32 v50, s14, v14
	s_ashr_i32 s15, s14, 31
	v_ashrrev_i32_e32 v51, 31, v50
	v_mov_b64_e32 v[52:53], s[4:5]
	v_lshl_add_u64 v[44:45], v[10:11], 0, s[4:5]
	v_lshl_add_u64 v[46:47], v[14:15], 0, s[14:15]
	v_lshl_add_u64 v[48:49], v[50:51], 2, s[76:77]
	v_mad_i64_i32 v[50:51], s[4:5], v50, s2, v[52:53]
	v_add_u32_e32 v93, s14, v25
	v_lshl_add_u64 v[46:47], v[46:47], 2, s[76:77]
	v_lshl_add_u64 v[50:51], v[10:11], 0, v[50:51]
	s_mov_b64 s[16:17], 0
	v_mov_b32_e32 v94, v61
	s_andn2_b64 vcc, exec, s[8:9]
	s_cbranch_vccnz .LBB0_21
	s_mov_b64 s[58:59], 0x4800
	v_mov_b32_e32 v234, v50
	v_mov_b32_e32 v235, v51
	v_mov_b32_e32 v236, v48
	v_mov_b32_e32 v237, v49
	global_load_dword v166, v[234:235], off nt
	v_lshl_add_u64 v[234:235], v[234:235], 0, s[58:59]
	global_load_dword v167, v[234:235], off nt
	v_lshl_add_u64 v[234:235], v[234:235], 0, s[58:59]
	global_load_dword v168, v[234:235], off nt
	v_lshl_add_u64 v[234:235], v[234:235], 0, s[58:59]
	global_load_dword v169, v[234:235], off nt
	v_lshl_add_u64 v[234:235], v[234:235], 0, s[58:59]
	global_load_dword v170, v[234:235], off nt
	v_lshl_add_u64 v[234:235], v[234:235], 0, s[58:59]
	global_load_dword v171, v[234:235], off nt
	v_lshl_add_u64 v[234:235], v[234:235], 0, s[58:59]
	global_load_dword v172, v[234:235], off nt
	v_lshl_add_u64 v[234:235], v[234:235], 0, s[58:59]
	global_load_dword v173, v[234:235], off nt
	v_lshl_add_u64 v[234:235], v[234:235], 0, s[58:59]
	global_load_dword v174, v[234:235], off nt
	v_lshl_add_u64 v[234:235], v[234:235], 0, s[58:59]
	global_load_dword v175, v[234:235], off nt
	v_lshl_add_u64 v[234:235], v[234:235], 0, s[58:59]
	global_load_dword v176, v[234:235], off nt
	v_lshl_add_u64 v[234:235], v[234:235], 0, s[58:59]
	global_load_dword v177, v[234:235], off nt
	v_lshl_add_u64 v[234:235], v[234:235], 0, s[58:59]
	global_load_dword v178, v[234:235], off nt
	v_lshl_add_u64 v[234:235], v[234:235], 0, s[58:59]
	global_load_dword v179, v[234:235], off nt
	v_lshl_add_u64 v[234:235], v[234:235], 0, s[58:59]
	global_load_dword v180, v[234:235], off nt
	v_lshl_add_u64 v[234:235], v[234:235], 0, s[58:59]
	global_load_dword v181, v[234:235], off nt
	v_lshl_add_u64 v[234:235], v[234:235], 0, s[58:59]
	global_load_dword v182, v[234:235], off nt
	v_lshl_add_u64 v[234:235], v[234:235], 0, s[58:59]
	global_load_dword v183, v[234:235], off nt
	v_lshl_add_u64 v[234:235], v[234:235], 0, s[58:59]
	global_load_dword v184, v[234:235], off nt
	v_lshl_add_u64 v[234:235], v[234:235], 0, s[58:59]
	global_load_dword v185, v[234:235], off nt
	v_lshl_add_u64 v[234:235], v[234:235], 0, s[58:59]
	global_load_dword v186, v[234:235], off nt
	v_lshl_add_u64 v[234:235], v[234:235], 0, s[58:59]
	global_load_dword v187, v[234:235], off nt
	v_lshl_add_u64 v[234:235], v[234:235], 0, s[58:59]
	global_load_dword v188, v[234:235], off nt
	v_lshl_add_u64 v[234:235], v[234:235], 0, s[58:59]
	global_load_dword v189, v[234:235], off nt
	v_lshl_add_u64 v[234:235], v[234:235], 0, s[58:59]
	global_load_dword v190, v[234:235], off nt
	v_lshl_add_u64 v[234:235], v[234:235], 0, s[58:59]
	global_load_dword v191, v[234:235], off nt
	v_lshl_add_u64 v[234:235], v[234:235], 0, s[58:59]
	global_load_dword v192, v[234:235], off nt
	v_lshl_add_u64 v[234:235], v[234:235], 0, s[58:59]
	global_load_dword v193, v[234:235], off nt
	v_lshl_add_u64 v[234:235], v[234:235], 0, s[58:59]
	global_load_dword v194, v[234:235], off nt
	v_lshl_add_u64 v[234:235], v[234:235], 0, s[58:59]
	global_load_dword v195, v[234:235], off nt
	v_lshl_add_u64 v[234:235], v[234:235], 0, s[58:59]
	global_load_dword v199, v[234:235], off nt
	v_lshl_add_u64 v[234:235], v[234:235], 0, s[58:59]
	global_load_dword v200, v[234:235], off nt
	global_load_dword v201, v[236:237], off
	global_load_dword v202, v[236:237], off offset:8
	global_load_dword v203, v[236:237], off offset:16
	global_load_dword v204, v[236:237], off offset:24
	global_load_dword v205, v[236:237], off offset:32
	global_load_dword v206, v[236:237], off offset:40
	global_load_dword v207, v[236:237], off offset:48
	global_load_dword v208, v[236:237], off offset:56
	global_load_dword v209, v[236:237], off offset:64
	global_load_dword v210, v[236:237], off offset:72
	global_load_dword v211, v[236:237], off offset:80
	global_load_dword v212, v[236:237], off offset:88
	global_load_dword v213, v[236:237], off offset:96
	global_load_dword v214, v[236:237], off offset:104
	global_load_dword v215, v[236:237], off offset:112
	global_load_dword v216, v[236:237], off offset:120
	global_load_dword v217, v[236:237], off offset:128
	global_load_dword v218, v[236:237], off offset:136
	global_load_dword v219, v[236:237], off offset:144
	global_load_dword v220, v[236:237], off offset:152
	global_load_dword v221, v[236:237], off offset:160
	global_load_dword v222, v[236:237], off offset:168
	global_load_dword v223, v[236:237], off offset:176
	global_load_dword v224, v[236:237], off offset:184
	global_load_dword v225, v[236:237], off offset:192
	global_load_dword v226, v[236:237], off offset:200
	global_load_dword v227, v[236:237], off offset:208
	global_load_dword v228, v[236:237], off offset:216
	global_load_dword v229, v[236:237], off offset:224
	global_load_dword v230, v[236:237], off offset:232
	global_load_dword v231, v[236:237], off offset:240
	global_load_dword v232, v[236:237], off offset:248
	s_waitcnt vmcnt(31)
; template <bool GU>
; __device__ __forceinline__ void transpose_item(const float* W, int K, int N, bf16* WT, const float* gs, LAS float* scr, int item, int lane) {
;     ...
;     for (int i = 0; i < 32; ++i) { const int kk = 2 * i + (lane >> 5); float w = W[(size_t)(k0 + kk) * N + n0 + (lane & 31)]; if (gs) w *= gs[k0 + kk]; scr[kk * 33 + (lane & 31)] = w; }
	v_mul_f32_e32 v166, v166, v201
	ds_write_b32 v94, v166
	s_waitcnt vmcnt(30)
	v_mul_f32_e32 v167, v167, v202
	ds_write_b32 v94, v167 offset:264
	s_waitcnt vmcnt(29)
	v_mul_f32_e32 v168, v168, v203
	ds_write_b32 v94, v168 offset:528
	s_waitcnt vmcnt(28)
	v_mul_f32_e32 v169, v169, v204
	ds_write_b32 v94, v169 offset:792
	s_waitcnt vmcnt(27)
	v_mul_f32_e32 v170, v170, v205
	ds_write_b32 v94, v170 offset:1056
	s_waitcnt vmcnt(26)
	v_mul_f32_e32 v171, v171, v206
	ds_write_b32 v94, v171 offset:1320
	s_waitcnt vmcnt(25)
	v_mul_f32_e32 v172, v172, v207
	ds_write_b32 v94, v172 offset:1584
	s_waitcnt vmcnt(24)
	v_mul_f32_e32 v173, v173, v208
	ds_write_b32 v94, v173 offset:1848
	s_waitcnt vmcnt(23)
	v_mul_f32_e32 v174, v174, v209
	ds_write_b32 v94, v174 offset:2112
	s_waitcnt vmcnt(22)
	v_mul_f32_e32 v175, v175, v210
	ds_write_b32 v94, v175 offset:2376
	s_waitcnt vmcnt(21)
	v_mul_f32_e32 v176, v176, v211
	ds_write_b32 v94, v176 offset:2640
	s_waitcnt vmcnt(20)
	v_mul_f32_e32 v177, v177, v212
	ds_write_b32 v94, v177 offset:2904
	s_waitcnt vmcnt(19)
	v_mul_f32_e32 v178, v178, v213
	ds_write_b32 v94, v178 offset:3168
	s_waitcnt vmcnt(18)
	v_mul_f32_e32 v179, v179, v214
	ds_write_b32 v94, v179 offset:3432
	s_waitcnt vmcnt(17)
	v_mul_f32_e32 v180, v180, v215
	ds_write_b32 v94, v180 offset:3696
	s_waitcnt vmcnt(16)
	v_mul_f32_e32 v181, v181, v216
	ds_write_b32 v94, v181 offset:3960
	s_waitcnt vmcnt(15)
	v_mul_f32_e32 v182, v182, v217
	ds_write_b32 v94, v182 offset:4224
	s_waitcnt vmcnt(14)
	v_mul_f32_e32 v183, v183, v218
	ds_write_b32 v94, v183 offset:4488
	s_waitcnt vmcnt(13)
	v_mul_f32_e32 v184, v184, v219
	ds_write_b32 v94, v184 offset:4752
	s_waitcnt vmcnt(12)
	v_mul_f32_e32 v185, v185, v220
	ds_write_b32 v94, v185 offset:5016
	s_waitcnt vmcnt(11)
	v_mul_f32_e32 v186, v186, v221
	ds_write_b32 v94, v186 offset:5280
	s_waitcnt vmcnt(10)
	v_mul_f32_e32 v187, v187, v222
	ds_write_b32 v94, v187 offset:5544
	s_waitcnt vmcnt(9)
	v_mul_f32_e32 v188, v188, v223
	ds_write_b32 v94, v188 offset:5808
	s_waitcnt vmcnt(8)
	v_mul_f32_e32 v189, v189, v224
	ds_write_b32 v94, v189 offset:6072
	s_waitcnt vmcnt(7)
	v_mul_f32_e32 v190, v190, v225
	ds_write_b32 v94, v190 offset:6336
	s_waitcnt vmcnt(6)
	v_mul_f32_e32 v191, v191, v226
	ds_write_b32 v94, v191 offset:6600
	s_waitcnt vmcnt(5)
	v_mul_f32_e32 v192, v192, v227
	ds_write_b32 v94, v192 offset:6864
	s_waitcnt vmcnt(4)
	v_mul_f32_e32 v193, v193, v228
	ds_write_b32 v94, v193 offset:7128
	s_waitcnt vmcnt(3)
	v_mul_f32_e32 v194, v194, v229
	ds_write_b32 v94, v194 offset:7392
	s_waitcnt vmcnt(2)
	v_mul_f32_e32 v195, v195, v230
	ds_write_b32 v94, v195 offset:7656
	s_waitcnt vmcnt(1)
	v_mul_f32_e32 v199, v199, v231
	ds_write_b32 v94, v199 offset:7920
	s_waitcnt vmcnt(0)
	v_mul_f32_e32 v200, v200, v232
	ds_write_b32 v94, v200 offset:8184
	s_branch .LBB0_14

; __device__ __forceinline__ unsigned cvt_pk(float lo, float hi) { unsigned r; asm("v_cvt_pk_bf16_f32 %0, %1, %2" : "=v"(r) : "v"(lo), "v"(hi)); return r; }
; __global__ void __launch_bounds__(NWAVES * 64, 2) mega_fwd(Args args) {
;     ...
;         for (int m0 = gw; m0 < MT; m0 += 2 * NGW) {
;             const int m1 = m0 + NGW; const bool has1 = m1 < MT;
;             const float* xr0 = (m0 < MP) ? x_p + (size_t)m0 * DM : x_s + (size_t)(m0 - MP) * DM;
;             const float* xr1 = has1 ? ((m1 < MP) ? x_p + (size_t)m1 * DM : x_s + (size_t)(m1 - MP) * DM) : xr0;
;             f32x4 a[2][4];
; #pragma unroll
;             for (int j = 0; j < 2; ++j) { a[0][2 * j] = *(const f32x4*)(xr0 + j * 512 + lane * 8); a[0][2 * j + 1] = *(const f32x4*)(xr0 + j * 512 + lane * 8 + 4);
;                                           a[1][2 * j] = *(const f32x4*)(xr1 + j * 512 + lane * 8); a[1][2 * j + 1] = *(const f32x4*)(xr1 + j * 512 + lane * 8 + 4); }
; #pragma unroll
;             for (int r = 0; r < 2; ++r) {
;                 const int m = r ? m1 : m0; float ss = 0.f;
; #pragma unroll
;                 for (int j = 0; j < 2; ++j) { const f32x4 p = a[r][2 * j], q = a[r][2 * j + 1];
;                     ss += (p[0] * p[0] + p[1] * p[1]) + (p[2] * p[2] + p[3] * p[3]) + (q[0] * q[0] + q[1] * q[1]) + (q[2] * q[2] + q[3] * q[3]);
;                     v4u w; w.x = cvt_pk(p[0], p[1]); w.y = cvt_pk(p[2], p[3]); w.z = cvt_pk(q[0], q[1]); w.w = cvt_pk(q[2], q[3]);
;                     if (r == 0 || has1) *(v4u*)(XB + (size_t)m * DM + j * 512 + lane * 8) = w; }
; #pragma unroll
;                 for (int o = 1; o < 64; o <<= 1) ss += __shfl_xor(ss, o);
;                 if (lane == 0 && (r == 0 || has1)) ssqb[m] = ss;
.LBB0_61:
	s_waitcnt lgkmcnt(0)
	v_lshl_add_u64 v[0:1], s[30:31], 0, v[22:23]
	global_load_dwordx4 v[16:19], v[0:1], off nt
	global_load_dwordx4 v[34:37], v[0:1], off offset:16 nt
	global_load_dwordx4 v[38:41], v[0:1], off offset:2048 nt
	global_load_dwordx4 v[44:47], v[0:1], off offset:2064 nt
	v_lshl_add_u64 v[8:9], s[28:29], 0, v[22:23]
	global_load_dwordx4 v[4:7], v[8:9], off offset:16 nt
	global_load_dwordx4 v[12:15], v[8:9], off nt
	global_load_dwordx4 v[0:3], v[8:9], off offset:2064 nt
	s_nop 0
	global_load_dwordx4 v[8:11], v[8:9], off offset:2048 nt
	s_lshl_b64 s[28:29], s[4:5], 11
	s_waitcnt vmcnt(7)
	v_mul_f32_e32 v24, v17, v17
	v_mul_f32_e32 v25, v19, v19
	s_waitcnt vmcnt(5)
	v_mul_f32_e32 v48, v39, v39
	v_mul_f32_e32 v49, v41, v41
	v_mul_f32_e32 v33, v35, v35
	s_waitcnt vmcnt(4)
	v_mul_f32_e32 v50, v45, v45
	v_fmac_f32_e32 v24, v16, v16
	v_fmac_f32_e32 v25, v18, v18
	v_fmac_f32_e32 v48, v38, v38
	v_fmac_f32_e32 v49, v40, v40
	v_mul_f32_e32 v42, v37, v37
	v_mul_f32_e32 v51, v47, v47
	v_fmac_f32_e32 v33, v34, v34
	v_fmac_f32_e32 v50, v44, v44
	v_add_f32_e32 v24, v24, v25
	v_add_f32_e32 v25, v48, v49
	v_fmac_f32_e32 v42, v36, v36
	v_fmac_f32_e32 v51, v46, v46
	v_add_f32_e32 v24, v24, v33
	v_add_f32_e32 v25, v25, v50
	v_add_f32_e32 v24, v42, v24
	v_add_f32_e32 v25, v51, v25
	v_add_f32_e32 v24, v24, v25
	ds_bpermute_b32 v25, v26, v24
	v_cvt_pk_bf16_f32 v16, v16, v17
	v_cvt_pk_bf16_f32 v17, v18, v19
	v_cvt_pk_bf16_f32 v18, v34, v35
	v_cvt_pk_bf16_f32 v19, v36, v37
	s_waitcnt lgkmcnt(0)
	v_add_f32_e32 v24, v24, v25
	ds_bpermute_b32 v25, v27, v24
	v_cvt_pk_bf16_f32 v34, v38, v39
	v_cvt_pk_bf16_f32 v35, v40, v41
	v_cvt_pk_bf16_f32 v36, v44, v45
	v_cvt_pk_bf16_f32 v37, v46, v47
	s_waitcnt lgkmcnt(0)
	v_add_f32_e32 v24, v24, v25
	ds_bpermute_b32 v25, v28, v24
	s_waitcnt lgkmcnt(0)
	v_add_f32_e32 v33, v24, v25
	ds_bpermute_b32 v42, v29, v33
	v_lshl_add_u64 v[24:25], v[20:21], 0, s[28:29]
	global_store_dwordx4 v[24:25], v[16:19], off
	global_store_dwordx4 v[24:25], v[34:37], off offset:1024
	s_waitcnt lgkmcnt(0)
	v_add_f32_e32 v33, v33, v42
	ds_bpermute_b32 v42, v30, v33
	s_waitcnt lgkmcnt(0)
	v_add_f32_e32 v16, v33, v42
	ds_bpermute_b32 v17, v31, v16
	s_and_saveexec_b64 s[28:29], s[0:1]
	s_cbranch_execz .LBB0_63
	s_lshl_b64 s[4:5], s[4:5], 2
	s_add_u32 s4, s2, s4
	s_waitcnt lgkmcnt(0)
	v_add_f32_e32 v16, v16, v17
	s_addc_u32 s5, s3, s5
	global_store_dword v32, v16, s[4:5]

; __device__ __forceinline__ unsigned cvt_pk(float lo, float hi) { unsigned r; asm("v_cvt_pk_bf16_f32 %0, %1, %2" : "=v"(r) : "v"(lo), "v"(hi)); return r; }
;     ...
;     for (size_t i = gtid * 8; i < NA; i += gth * 8) {
;         const size_t gi = (size_t)l * NA + i;
;         const f32x4 a = *(const f32x4*)(I.cak + gi), b = *(const f32x4*)(I.cak + gi + 4), c = *(const f32x4*)(I.cav + gi), d = *(const f32x4*)(I.cav + gi + 4);
;         v4u w; w.x = cvt_pk(a[0], a[1]); w.y = cvt_pk(a[2], a[3]); w.z = cvt_pk(b[0], b[1]); w.w = cvt_pk(b[2], b[3]);
;         *(v4u*)((bf16*)(ws + WS_CKA) + gi) = w;
;         w.x = cvt_pk(c[0], c[1]); w.y = cvt_pk(c[2], c[3]); w.z = cvt_pk(d[0], d[1]); w.w = cvt_pk(d[2], d[3]);
;         *(v4u*)((bf16*)(ws + WS_CVA) + gi) = w;
;         if (((i >> 9) & 511) >= 64) { float* dk = out + O_AKS + gi - 32768; float* dv = out + O_AVS + gi - 32768;
;             *(f32x4*)dk = a; *(f32x4*)(dk + 4) = b; *(f32x4*)dv = c; *(f32x4*)(dv + 4) = d; }
;     }
.LBB0_294:
	v_lshl_add_u64 v[0:1], s[12:13], 0, v[18:19]
	global_load_dwordx4 v[4:7], v[0:1], off offset:-16 nt
	s_nop 0
	global_load_dwordx4 v[0:3], v[0:1], off nt
	v_lshl_add_u64 v[8:9], s[14:15], 0, v[18:19]
	s_waitcnt lgkmcnt(0)
	global_load_dwordx4 v[12:15], v[8:9], off offset:-16 nt
	s_nop 0
	global_load_dwordx4 v[8:11], v[8:9], off nt
	v_add_co_u32_e32 v36, vcc, 0x1000000, v22
	v_and_b32_e32 v24, 0x38000, v26
	s_nop 0
	v_addc_co_u32_e32 v37, vcc, 0, v23, vcc
	v_cmp_ne_u64_e32 vcc, 0, v[24:25]
	s_waitcnt vmcnt(3)
	v_cvt_pk_bf16_f32 v28, v4, v5
	v_cvt_pk_bf16_f32 v29, v6, v7
	s_waitcnt vmcnt(2)
	v_cvt_pk_bf16_f32 v30, v0, v1
	v_cvt_pk_bf16_f32 v31, v2, v3
	s_waitcnt vmcnt(1)
	v_cvt_pk_bf16_f32 v32, v12, v13
	v_cvt_pk_bf16_f32 v33, v14, v15
	s_waitcnt vmcnt(0)
	v_cvt_pk_bf16_f32 v34, v8, v9
	v_cvt_pk_bf16_f32 v35, v10, v11
	global_store_dwordx4 v[22:23], v[28:31], off
	global_store_dwordx4 v[36:37], v[32:35], off
	s_and_saveexec_b64 s[52:53], vcc
	s_cbranch_execz .LBB0_293
	v_lshl_add_u64 v[28:29], s[42:43], 0, v[18:19]
	v_add_co_u32_e32 v30, vcc, 0x8c60000, v28
	s_nop 1
	v_addc_co_u32_e32 v31, vcc, 0, v29, vcc
	global_store_dwordx4 v[30:31], v[4:7], off
	global_store_dwordx4 v[30:31], v[0:3], off offset:16
	s_nop 1
	v_add_co_u32_e32 v0, vcc, 0xac60000, v28
	s_nop 1
	v_addc_co_u32_e32 v1, vcc, 0, v29, vcc
	global_store_dwordx4 v[0:1], v[12:15], off
	global_store_dwordx4 v[0:1], v[8:11], off offset:16
	s_branch .LBB0_293

; __device__ __forceinline__ unsigned cvt_pk(float lo, float hi) { unsigned r; asm("v_cvt_pk_bf16_f32 %0, %1, %2" : "=v"(r) : "v"(lo), "v"(hi)); return r; }
;     ...
;     for (size_t i = gtid * 8; i < NB; i += gth * 8) {
;         const size_t gi = (size_t)l * NB + i;
;         const f32x4 a = *(const f32x4*)(I.cbk + gi), b = *(const f32x4*)(I.cbk + gi + 4), c = *(const f32x4*)(I.cbv + gi), d = *(const f32x4*)(I.cbv + gi + 4);
;         v4u w; w.x = cvt_pk(a[0], a[1]); w.y = cvt_pk(a[2], a[3]); w.z = cvt_pk(b[0], b[1]); w.w = cvt_pk(b[2], b[3]);
;         *(v4u*)((bf16*)(ws + WS_CKB) + gi) = w;
;         w.x = cvt_pk(c[0], c[1]); w.y = cvt_pk(c[2], c[3]); w.z = cvt_pk(d[0], d[1]); w.w = cvt_pk(d[2], d[3]);
;         *(v4u*)((bf16*)(ws + WS_CVB) + gi) = w;
;         if (((i >> 7) & 127) >= 64) { float* dk = out + O_BKS + gi - 8192; float* dv = out + O_BVS + gi - 8192;
;             *(f32x4*)dk = a; *(f32x4*)(dk + 4) = b; *(f32x4*)dv = c; *(f32x4*)(dv + 4) = d; }
;     }
.LBB0_299:
	v_lshl_add_u64 v[0:1], s[12:13], 0, v[18:19]
	global_load_dwordx4 v[4:7], v[0:1], off offset:-16 nt
	s_nop 0
	global_load_dwordx4 v[0:3], v[0:1], off nt
	v_lshl_add_u64 v[8:9], s[6:7], 0, v[18:19]
	s_waitcnt lgkmcnt(0)
	global_load_dwordx4 v[12:15], v[8:9], off offset:-16 nt
	s_nop 0
	global_load_dwordx4 v[8:11], v[8:9], off nt
	v_add_co_u32_e32 v30, vcc, 0x100000, v20
	v_and_b32_e32 v32, 0x2000, v16
	s_nop 0
	v_addc_co_u32_e32 v31, vcc, 0, v21, vcc
	v_cmp_ne_u32_e32 vcc, 0, v32
	s_waitcnt vmcnt(3)
	v_cvt_pk_bf16_f32 v22, v4, v5
	v_cvt_pk_bf16_f32 v23, v6, v7
	s_waitcnt vmcnt(2)
	v_cvt_pk_bf16_f32 v24, v0, v1
	v_cvt_pk_bf16_f32 v25, v2, v3
	s_waitcnt vmcnt(1)
	v_cvt_pk_bf16_f32 v26, v12, v13
	v_cvt_pk_bf16_f32 v27, v14, v15
	s_waitcnt vmcnt(0)
	v_cvt_pk_bf16_f32 v28, v8, v9
	v_cvt_pk_bf16_f32 v29, v10, v11
	global_store_dwordx4 v[20:21], v[22:25], off
	global_store_dwordx4 v[30:31], v[26:29], off
	s_and_saveexec_b64 s[42:43], vcc
	s_cbranch_execz .LBB0_298
	v_lshl_add_u64 v[22:23], s[40:41], 0, v[18:19]
	v_add_co_u32_e32 v24, vcc, 0xcc78000, v22
	s_nop 1
	v_addc_co_u32_e32 v25, vcc, 0, v23, vcc
	global_store_dwordx4 v[24:25], v[4:7], off
	global_store_dwordx4 v[24:25], v[0:3], off offset:16
	s_nop 1
	v_add_co_u32_e32 v0, vcc, 0xce78000, v22
	s_nop 1
	v_addc_co_u32_e32 v1, vcc, 0, v23, vcc
	global_store_dwordx4 v[0:1], v[12:15], off
	global_store_dwordx4 v[0:1], v[8:11], off offset:16
	s_branch .LBB0_298

; __device__ __forceinline__ unsigned cvt_pk(float lo, float hi) { unsigned r; asm("v_cvt_pk_bf16_f32 %0, %1, %2" : "=v"(r) : "v"(lo), "v"(hi)); return r; }
; __device__ __forceinline__ void convert_flat(const float* src, bf16* dst, size_t n, size_t gtid, size_t gthreads) {
;     for (size_t i = gtid * 8; i < n; i += gthreads * 8) {
;         const f32x4 a = *(const f32x4*)(src + i), b = *(const f32x4*)(src + i + 4);
;         v4u w; w.x = cvt_pk(a[0], a[1]); w.y = cvt_pk(a[2], a[3]); w.z = cvt_pk(b[0], b[1]); w.w = cvt_pk(b[2], b[3]);
;         *(v4u*)(dst + i) = w;
;     }
; }
.LBB0_414:
	global_load_dwordx4 v[12:15], v[6:7], off offset:-16 nt
	global_load_dwordx4 v[16:19], v[6:7], off nt
	v_lshl_add_u64 v[10:11], v[10:11], 0, s[6:7]
	v_cmp_lt_u64_e32 vcc, s[28:29], v[10:11]
	v_lshl_add_u64 v[6:7], v[6:7], 0, s[10:11]
	s_or_b64 s[14:15], vcc, s[14:15]
	s_waitcnt vmcnt(1)
	v_cvt_pk_bf16_f32 v12, v12, v13
	v_cvt_pk_bf16_f32 v13, v14, v15
	s_waitcnt vmcnt(0)
	v_cvt_pk_bf16_f32 v14, v16, v17
	v_cvt_pk_bf16_f32 v15, v18, v19
	global_store_dwordx4 v[8:9], v[12:15], off
	v_lshl_add_u64 v[8:9], v[8:9], 0, s[12:13]
	s_andn2_b64 exec, exec, s[14:15]
	s_cbranch_execnz .LBB0_414

; __device__ __forceinline__ unsigned cvt_pk(float lo, float hi) { unsigned r; asm("v_cvt_pk_bf16_f32 %0, %1, %2" : "=v"(r) : "v"(lo), "v"(hi)); return r; }
; __device__ __forceinline__ void convert_flat(const float* src, bf16* dst, size_t n, size_t gtid, size_t gthreads) {
;     for (size_t i = gtid * 8; i < n; i += gthreads * 8) {
;         const f32x4 a = *(const f32x4*)(src + i), b = *(const f32x4*)(src + i + 4);
;         v4u w; w.x = cvt_pk(a[0], a[1]); w.y = cvt_pk(a[2], a[3]); w.z = cvt_pk(b[0], b[1]); w.w = cvt_pk(b[2], b[3]);
;         *(v4u*)(dst + i) = w;
;     }
; }
.LBB0_417:
	global_load_dwordx4 v[6:9], v[4:5], off offset:-16 nt
	global_load_dwordx4 v[10:13], v[4:5], off nt
	v_lshl_add_u64 v[0:1], v[0:1], 0, s[6:7]
	v_cmp_lt_u64_e32 vcc, s[28:29], v[0:1]
	v_lshl_add_u64 v[4:5], v[4:5], 0, s[10:11]
	s_or_b64 s[14:15], vcc, s[14:15]
	s_waitcnt vmcnt(1)
	v_cvt_pk_bf16_f32 v6, v6, v7
	v_cvt_pk_bf16_f32 v7, v8, v9
	s_waitcnt vmcnt(0)
	v_cvt_pk_bf16_f32 v8, v10, v11
	v_cvt_pk_bf16_f32 v9, v12, v13
	global_store_dwordx4 v[2:3], v[6:9], off
	v_lshl_add_u64 v[2:3], v[2:3], 0, s[12:13]
	s_andn2_b64 exec, exec, s[14:15]
	s_cbranch_execnz .LBB0_417

; #define LAS __attribute__((address_space(3)))
; template <bool GU>
; __device__ __forceinline__ void transpose_item(const float* W, int K, int N, bf16* WT, const float* gs, LAS float* scr, int item, int lane) {
;     const int nblk = N / 32, kb = item / nblk, nb = item % nblk, k0 = 64 * kb, n0 = 32 * nb;
; #pragma unroll 16
;     for (int i = 0; i < 32; ++i) { const int kk = 2 * i + (lane >> 5); float w = W[(size_t)(k0 + kk) * N + n0 + (lane & 31)]; if (gs) w *= gs[k0 + kk]; scr[kk * 33 + (lane & 31)] = w; }
;     asm volatile("s_waitcnt lgkmcnt(0)" ::: "memory");
;     int d0 = n0;
;     if (GU) { const int f = (n0 < FF) ? n0 : n0 - FF; d0 = 256 * (f >> 7) + (f & 127) + ((n0 < FF) ? 0 : 128); }
; __device__ __forceinline__ void conv_weights(LAS unsigned char* lds, unsigned char* ws, const PIn& I, const int l, const int wave, const int lane, const int gw, const int NGW, const int r_lo, const int r_hi) {
;     ...
;         if (r < I_GU) { transpose_item<true>(I.w_gu + (size_t)l * DM * 2 * FF, DM, 2 * FF, (bf16*)(wb + W_GU), I.g_ffn + l * DM, scr, r, lane); continue; } r -= I_GU;
.LBB0_497:
	s_andn2_b64 vcc, exec, s[6:7]
	s_cbranch_vccnz .LBB0_533
	s_add_i32 s6, s1, 0xf980
	s_and_b32 s30, s6, 0xffff
	s_mul_i32 s7, s30, 0xba2f
	s_lshr_b32 s7, s7, 23
	s_mul_i32 s9, s7, 0xb0
	s_sub_i32 s29, s6, s9
	s_lshl_b32 s6, s29, 7
	s_lshl_b32 s9, s7, 6
	s_and_b32 s10, s6, 0x3ff80
	v_add_u32_e32 v60, s9, v37
	v_mov_b64_e32 v[94:95], s[10:11]
	v_mad_i64_i32 v[60:61], s[6:7], v60, s3, v[94:95]
	s_mul_hi_u32 s6, s30, 0x1745d18
	v_add_u32_e32 v64, s9, v36
	v_add_u32_e32 v66, s9, v35
	v_add_u32_e32 v68, s9, v34
	v_add_u32_e32 v70, s9, v33
	v_add_u32_e32 v72, s9, v32
	v_add_u32_e32 v74, s9, v31
	v_add_u32_e32 v76, s9, v30
	v_add_u32_e32 v78, s9, v29
	v_add_u32_e32 v80, s9, v28
	v_add_u32_e32 v82, s9, v27
	v_add_u32_e32 v84, s9, v26
	v_add_u32_e32 v86, s9, v25
	v_add_u32_e32 v88, s9, v24
	v_add_u32_e32 v90, s9, v1
	v_add_u32_e32 v96, s9, v54
	v_readlane_b32 s48, v249, 21
	s_lshl_b32 s10, s6, 8
	v_mad_i64_i32 v[64:65], s[6:7], v64, s3, v[94:95]
	v_mad_i64_i32 v[66:67], s[6:7], v66, s3, v[94:95]
	v_mad_i64_i32 v[68:69], s[6:7], v68, s3, v[94:95]
	v_mad_i64_i32 v[70:71], s[6:7], v70, s3, v[94:95]
	v_mad_i64_i32 v[72:73], s[6:7], v72, s3, v[94:95]
	v_mad_i64_i32 v[74:75], s[6:7], v74, s3, v[94:95]
	v_mad_i64_i32 v[76:77], s[6:7], v76, s3, v[94:95]
	v_mad_i64_i32 v[78:79], s[6:7], v78, s3, v[94:95]
	v_mad_i64_i32 v[80:81], s[6:7], v80, s3, v[94:95]
	v_mad_i64_i32 v[82:83], s[6:7], v82, s3, v[94:95]
	v_mad_i64_i32 v[84:85], s[6:7], v84, s3, v[94:95]
	v_mad_i64_i32 v[86:87], s[6:7], v86, s3, v[94:95]
	v_mad_i64_i32 v[88:89], s[6:7], v88, s3, v[94:95]
	v_mad_i64_i32 v[90:91], s[6:7], v90, s3, v[94:95]
	v_ashrrev_i32_e32 v97, 31, v96
	v_mad_i64_i32 v[94:95], s[6:7], v96, s3, v[94:95]
	v_readlane_b32 s62, v249, 35
	v_readlane_b32 s63, v249, 36
	s_lshl_b32 s36, s29, 5
	v_lshl_add_u64 v[60:61], v[56:57], 0, v[60:61]
	v_lshl_add_u64 v[62:63], v[58:59], 0, s[10:11]
	v_lshl_add_u64 v[64:65], v[56:57], 0, v[64:65]
	v_lshl_add_u64 v[66:67], v[56:57], 0, v[66:67]
	v_lshl_add_u64 v[68:69], v[56:57], 0, v[68:69]
	v_lshl_add_u64 v[70:71], v[56:57], 0, v[70:71]
	v_lshl_add_u64 v[72:73], v[56:57], 0, v[72:73]
	v_lshl_add_u64 v[74:75], v[56:57], 0, v[74:75]
	v_lshl_add_u64 v[76:77], v[56:57], 0, v[76:77]
	v_lshl_add_u64 v[78:79], v[56:57], 0, v[78:79]
	v_lshl_add_u64 v[80:81], v[56:57], 0, v[80:81]
	v_lshl_add_u64 v[82:83], v[56:57], 0, v[82:83]
	v_lshl_add_u64 v[84:85], v[56:57], 0, v[84:85]
	v_lshl_add_u64 v[86:87], v[56:57], 0, v[86:87]
	v_lshl_add_u64 v[88:89], v[56:57], 0, v[88:89]
	v_lshl_add_u64 v[90:91], v[56:57], 0, v[90:91]
	v_lshlrev_b64 v[92:93], 2, v[96:97]
	v_lshl_add_u64 v[94:95], v[56:57], 0, v[94:95]
	s_mov_b64 s[30:31], 0
	s_mov_b64 s[42:43], s[62:63]
	v_mov_b32_e32 v137, v136
	v_readlane_b32 s49, v249, 22
	v_readlane_b32 s50, v249, 23
	v_readlane_b32 s51, v249, 24
	v_readlane_b32 s52, v249, 25
	v_readlane_b32 s53, v249, 26
	v_readlane_b32 s54, v249, 27
	v_readlane_b32 s55, v249, 28
	v_readlane_b32 s56, v249, 29
	v_readlane_b32 s57, v249, 30
	v_readlane_b32 s58, v249, 31
	v_readlane_b32 s59, v249, 32
	v_readlane_b32 s60, v249, 33
	v_readlane_b32 s61, v249, 34
	s_andn2_b64 vcc, exec, s[12:13]
	s_cbranch_vccnz .LBB0_500
	s_mov_b64 s[58:59], 0xb000
	v_mov_b32_e32 v234, v94
	v_mov_b32_e32 v235, v95
	v_lshl_add_u64 v[236:237], s[42:43], 0, v[92:93]
	global_load_dword v166, v[234:235], off nt
	v_lshl_add_u64 v[234:235], v[234:235], 0, s[58:59]
	global_load_dword v167, v[234:235], off nt
	v_lshl_add_u64 v[234:235], v[234:235], 0, s[58:59]
	global_load_dword v168, v[234:235], off nt
	v_lshl_add_u64 v[234:235], v[234:235], 0, s[58:59]
	global_load_dword v169, v[234:235], off nt
	v_lshl_add_u64 v[234:235], v[234:235], 0, s[58:59]
	global_load_dword v170, v[234:235], off nt
	v_lshl_add_u64 v[234:235], v[234:235], 0, s[58:59]
	global_load_dword v171, v[234:235], off nt
	v_lshl_add_u64 v[234:235], v[234:235], 0, s[58:59]
	global_load_dword v172, v[234:235], off nt
	v_lshl_add_u64 v[234:235], v[234:235], 0, s[58:59]
	global_load_dword v173, v[234:235], off nt
	v_lshl_add_u64 v[234:235], v[234:235], 0, s[58:59]
	global_load_dword v174, v[234:235], off nt
	v_lshl_add_u64 v[234:235], v[234:235], 0, s[58:59]
	global_load_dword v175, v[234:235], off nt
	v_lshl_add_u64 v[234:235], v[234:235], 0, s[58:59]
	global_load_dword v176, v[234:235], off nt
	v_lshl_add_u64 v[234:235], v[234:235], 0, s[58:59]
	global_load_dword v177, v[234:235], off nt
	v_lshl_add_u64 v[234:235], v[234:235], 0, s[58:59]
	global_load_dword v178, v[234:235], off nt
	v_lshl_add_u64 v[234:235], v[234:235], 0, s[58:59]
	global_load_dword v179, v[234:235], off nt
	v_lshl_add_u64 v[234:235], v[234:235], 0, s[58:59]
	global_load_dword v180, v[234:235], off nt
	v_lshl_add_u64 v[234:235], v[234:235], 0, s[58:59]
	global_load_dword v181, v[234:235], off nt
	v_lshl_add_u64 v[234:235], v[234:235], 0, s[58:59]
	global_load_dword v182, v[234:235], off nt
	v_lshl_add_u64 v[234:235], v[234:235], 0, s[58:59]
	global_load_dword v183, v[234:235], off nt
	v_lshl_add_u64 v[234:235], v[234:235], 0, s[58:59]
	global_load_dword v184, v[234:235], off nt
	v_lshl_add_u64 v[234:235], v[234:235], 0, s[58:59]
	global_load_dword v185, v[234:235], off nt
	v_lshl_add_u64 v[234:235], v[234:235], 0, s[58:59]
	global_load_dword v186, v[234:235], off nt
	v_lshl_add_u64 v[234:235], v[234:235], 0, s[58:59]
	global_load_dword v187, v[234:235], off nt
	v_lshl_add_u64 v[234:235], v[234:235], 0, s[58:59]
; template <bool GU>
; __device__ __forceinline__ void transpose_item(const float* W, int K, int N, bf16* WT, const float* gs, LAS float* scr, int item, int lane) {
;     ...
;     for (int i = 0; i < 32; ++i) { const int kk = 2 * i + (lane >> 5); float w = W[(size_t)(k0 + kk) * N + n0 + (lane & 31)]; if (gs) w *= gs[k0 + kk]; scr[kk * 33 + (lane & 31)] = w; }
	global_load_dword v188, v[234:235], off nt
	v_lshl_add_u64 v[234:235], v[234:235], 0, s[58:59]
	global_load_dword v189, v[234:235], off nt
	v_lshl_add_u64 v[234:235], v[234:235], 0, s[58:59]
	global_load_dword v190, v[234:235], off nt
	v_lshl_add_u64 v[234:235], v[234:235], 0, s[58:59]
	global_load_dword v191, v[234:235], off nt
	v_lshl_add_u64 v[234:235], v[234:235], 0, s[58:59]
	global_load_dword v192, v[234:235], off nt
	v_lshl_add_u64 v[234:235], v[234:235], 0, s[58:59]
	global_load_dword v193, v[234:235], off nt
	v_lshl_add_u64 v[234:235], v[234:235], 0, s[58:59]
	global_load_dword v194, v[234:235], off nt
	v_lshl_add_u64 v[234:235], v[234:235], 0, s[58:59]
	global_load_dword v195, v[234:235], off nt
	v_lshl_add_u64 v[234:235], v[234:235], 0, s[58:59]
	global_load_dword v199, v[234:235], off nt
	v_lshl_add_u64 v[234:235], v[234:235], 0, s[58:59]
	global_load_dword v200, v[234:235], off nt
	global_load_dword v201, v[236:237], off
	global_load_dword v202, v[236:237], off offset:8
	global_load_dword v203, v[236:237], off offset:16
	global_load_dword v204, v[236:237], off offset:24
	global_load_dword v205, v[236:237], off offset:32
	global_load_dword v206, v[236:237], off offset:40
	global_load_dword v207, v[236:237], off offset:48
	global_load_dword v208, v[236:237], off offset:56
	global_load_dword v209, v[236:237], off offset:64
	global_load_dword v210, v[236:237], off offset:72
	global_load_dword v211, v[236:237], off offset:80
	global_load_dword v212, v[236:237], off offset:88
	global_load_dword v213, v[236:237], off offset:96
	global_load_dword v214, v[236:237], off offset:104
	global_load_dword v215, v[236:237], off offset:112
	global_load_dword v216, v[236:237], off offset:120
	global_load_dword v217, v[236:237], off offset:128
	global_load_dword v218, v[236:237], off offset:136
	global_load_dword v219, v[236:237], off offset:144
	global_load_dword v220, v[236:237], off offset:152
	global_load_dword v221, v[236:237], off offset:160
	global_load_dword v222, v[236:237], off offset:168
	global_load_dword v223, v[236:237], off offset:176
	global_load_dword v224, v[236:237], off offset:184
	global_load_dword v225, v[236:237], off offset:192
	global_load_dword v226, v[236:237], off offset:200
	global_load_dword v227, v[236:237], off offset:208
	global_load_dword v228, v[236:237], off offset:216
	global_load_dword v229, v[236:237], off offset:224
	global_load_dword v230, v[236:237], off offset:232
	global_load_dword v231, v[236:237], off offset:240
	global_load_dword v232, v[236:237], off offset:248
	s_waitcnt vmcnt(31)
	v_mul_f32_e32 v166, v166, v201
	ds_write_b32 v137, v166
	s_waitcnt vmcnt(30)
	v_mul_f32_e32 v167, v167, v202
	ds_write_b32 v137, v167 offset:264
	s_waitcnt vmcnt(29)
	v_mul_f32_e32 v168, v168, v203
	ds_write_b32 v137, v168 offset:528
	s_waitcnt vmcnt(28)
	v_mul_f32_e32 v169, v169, v204
	ds_write_b32 v137, v169 offset:792
	s_waitcnt vmcnt(27)
	v_mul_f32_e32 v170, v170, v205
	ds_write_b32 v137, v170 offset:1056
	s_waitcnt vmcnt(26)
	v_mul_f32_e32 v171, v171, v206
	ds_write_b32 v137, v171 offset:1320
	s_waitcnt vmcnt(25)
	v_mul_f32_e32 v172, v172, v207
	ds_write_b32 v137, v172 offset:1584
	s_waitcnt vmcnt(24)
	v_mul_f32_e32 v173, v173, v208
	ds_write_b32 v137, v173 offset:1848
	s_waitcnt vmcnt(23)
	v_mul_f32_e32 v174, v174, v209
	ds_write_b32 v137, v174 offset:2112
	s_waitcnt vmcnt(22)
	v_mul_f32_e32 v175, v175, v210
	ds_write_b32 v137, v175 offset:2376
	s_waitcnt vmcnt(21)
	v_mul_f32_e32 v176, v176, v211
	ds_write_b32 v137, v176 offset:2640
	s_waitcnt vmcnt(20)
	v_mul_f32_e32 v177, v177, v212
	ds_write_b32 v137, v177 offset:2904
	s_waitcnt vmcnt(19)
	v_mul_f32_e32 v178, v178, v213
	ds_write_b32 v137, v178 offset:3168
	s_waitcnt vmcnt(18)
	v_mul_f32_e32 v179, v179, v214
	ds_write_b32 v137, v179 offset:3432
	s_waitcnt vmcnt(17)
	v_mul_f32_e32 v180, v180, v215
	ds_write_b32 v137, v180 offset:3696
	s_waitcnt vmcnt(16)
	v_mul_f32_e32 v181, v181, v216
	ds_write_b32 v137, v181 offset:3960
	s_waitcnt vmcnt(15)
	v_mul_f32_e32 v182, v182, v217
	ds_write_b32 v137, v182 offset:4224
	s_waitcnt vmcnt(14)
	v_mul_f32_e32 v183, v183, v218
	ds_write_b32 v137, v183 offset:4488
	s_waitcnt vmcnt(13)
	v_mul_f32_e32 v184, v184, v219
	ds_write_b32 v137, v184 offset:4752
	s_waitcnt vmcnt(12)
	v_mul_f32_e32 v185, v185, v220
	ds_write_b32 v137, v185 offset:5016
	s_waitcnt vmcnt(11)
	v_mul_f32_e32 v186, v186, v221
	ds_write_b32 v137, v186 offset:5280
	s_waitcnt vmcnt(10)
	v_mul_f32_e32 v187, v187, v222
	ds_write_b32 v137, v187 offset:5544
	s_waitcnt vmcnt(9)
	v_mul_f32_e32 v188, v188, v223
	ds_write_b32 v137, v188 offset:5808
	s_waitcnt vmcnt(8)
	v_mul_f32_e32 v189, v189, v224
	ds_write_b32 v137, v189 offset:6072
	s_waitcnt vmcnt(7)
	v_mul_f32_e32 v190, v190, v225
	ds_write_b32 v137, v190 offset:6336
	s_waitcnt vmcnt(6)
	v_mul_f32_e32 v191, v191, v226
	ds_write_b32 v137, v191 offset:6600
	s_waitcnt vmcnt(5)
	v_mul_f32_e32 v192, v192, v227
	ds_write_b32 v137, v192 offset:6864
	s_waitcnt vmcnt(4)
	v_mul_f32_e32 v193, v193, v228
	ds_write_b32 v137, v193 offset:7128
	s_waitcnt vmcnt(3)
	v_mul_f32_e32 v194, v194, v229
	ds_write_b32 v137, v194 offset:7392
	s_waitcnt vmcnt(2)
	v_mul_f32_e32 v195, v195, v230
	ds_write_b32 v137, v195 offset:7656
	s_waitcnt vmcnt(1)
	v_mul_f32_e32 v199, v199, v231
	ds_write_b32 v137, v199 offset:7920
	s_waitcnt vmcnt(0)
	v_mul_f32_e32 v200, v200, v232
	ds_write_b32 v137, v200 offset:8184
	s_branch .LBB0_532

; __device__ __forceinline__ unsigned cvt_pk(float lo, float hi) { unsigned r; asm("v_cvt_pk_bf16_f32 %0, %1, %2" : "=v"(r) : "v"(lo), "v"(hi)); return r; }
; __device__ __forceinline__ void convert_flat(const float* src, bf16* dst, size_t n, size_t gtid, size_t gthreads) {
;     for (size_t i = gtid * 8; i < n; i += gthreads * 8) {
;         const f32x4 a = *(const f32x4*)(src + i), b = *(const f32x4*)(src + i + 4);
;         v4u w; w.x = cvt_pk(a[0], a[1]); w.y = cvt_pk(a[2], a[3]); w.z = cvt_pk(b[0], b[1]); w.w = cvt_pk(b[2], b[3]);
;         *(v4u*)(dst + i) = w;
;     }
; }
.LBB0_619:
	global_load_dwordx4 v[12:15], v[6:7], off nt
	global_load_dwordx4 v[16:19], v[6:7], off offset:16 nt
	v_lshl_add_u64 v[10:11], v[10:11], 0, s[6:7]
	v_cmp_lt_u64_e32 vcc, s[42:43], v[10:11]
	v_lshl_add_u64 v[6:7], v[6:7], 0, s[14:15]
	s_or_b64 s[30:31], vcc, s[30:31]
	s_waitcnt vmcnt(1)
	v_cvt_pk_bf16_f32 v12, v12, v13
	v_cvt_pk_bf16_f32 v13, v14, v15
	s_waitcnt vmcnt(0)
	v_cvt_pk_bf16_f32 v14, v16, v17
	v_cvt_pk_bf16_f32 v15, v18, v19
	global_store_dwordx4 v[8:9], v[12:15], off
	v_lshl_add_u64 v[8:9], v[8:9], 0, s[16:17]
	s_andn2_b64 exec, exec, s[30:31]
	s_cbranch_execnz .LBB0_619

; __device__ __forceinline__ unsigned cvt_pk(float lo, float hi) { unsigned r; asm("v_cvt_pk_bf16_f32 %0, %1, %2" : "=v"(r) : "v"(lo), "v"(hi)); return r; }
; __device__ __forceinline__ void convert_flat(const float* src, bf16* dst, size_t n, size_t gtid, size_t gthreads) {
;     for (size_t i = gtid * 8; i < n; i += gthreads * 8) {
;         const f32x4 a = *(const f32x4*)(src + i), b = *(const f32x4*)(src + i + 4);
;         v4u w; w.x = cvt_pk(a[0], a[1]); w.y = cvt_pk(a[2], a[3]); w.z = cvt_pk(b[0], b[1]); w.w = cvt_pk(b[2], b[3]);
;         *(v4u*)(dst + i) = w;
;     }
; }
.LBB0_622:
	global_load_dwordx4 v[6:9], v[4:5], off nt
	global_load_dwordx4 v[10:13], v[4:5], off offset:16 nt
	v_lshl_add_u64 v[0:1], v[0:1], 0, s[6:7]
	v_cmp_lt_u64_e32 vcc, s[18:19], v[0:1]
	v_lshl_add_u64 v[4:5], v[4:5], 0, s[14:15]
	s_or_b64 s[16:17], vcc, s[16:17]
	s_waitcnt vmcnt(1)
	v_cvt_pk_bf16_f32 v6, v6, v7
	v_cvt_pk_bf16_f32 v7, v8, v9
	s_waitcnt vmcnt(0)
	v_cvt_pk_bf16_f32 v8, v10, v11
	v_cvt_pk_bf16_f32 v9, v12, v13
	global_store_dwordx4 v[2:3], v[6:9], off
	v_lshl_add_u64 v[2:3], v[2:3], 0, s[10:11]
	s_andn2_b64 exec, exec, s[16:17]
	s_cbranch_execnz .LBB0_622

; #define LAS __attribute__((address_space(3)))
; template <bool GU>
; __device__ __forceinline__ void transpose_item(const float* W, int K, int N, bf16* WT, const float* gs, LAS float* scr, int item, int lane) {
;     const int nblk = N / 32, kb = item / nblk, nb = item % nblk, k0 = 64 * kb, n0 = 32 * nb;
; #pragma unroll 16
;     for (int i = 0; i < 32; ++i) { const int kk = 2 * i + (lane >> 5); float w = W[(size_t)(k0 + kk) * N + n0 + (lane & 31)]; if (gs) w *= gs[k0 + kk]; scr[kk * 33 + (lane & 31)] = w; }
;     asm volatile("s_waitcnt lgkmcnt(0)" ::: "memory");
;     int d0 = n0;
;     if (GU) { const int f = (n0 < FF) ? n0 : n0 - FF; d0 = 256 * (f >> 7) + (f & 127) + ((n0 < FF) ? 0 : 128); }
; __device__ __forceinline__ void conv_weights(LAS unsigned char* lds, unsigned char* ws, const PIn& I, const int l, const int wave, const int lane, const int gw, const int NGW, const int r_lo, const int r_hi) {
;     ...
;         if (r < I_GU) { transpose_item<true>(I.w_gu + (size_t)l * DM * 2 * FF, DM, 2 * FF, (bf16*)(wb + W_GU), I.g_ffn + l * DM, scr, r, lane); continue; } r -= I_GU;
.LBB0_718:
	s_andn2_b64 vcc, exec, s[6:7]
	s_cbranch_vccnz .LBB0_754
	s_add_i32 s6, s0, 0xf980
	s_and_b32 s10, s6, 0xffff
	s_mul_i32 s7, s10, 0xba2f
	s_lshr_b32 s7, s7, 23
	s_mul_i32 s40, s7, 0xb0
	s_sub_i32 s41, s6, s40
	s_lshl_b32 s6, s41, 7
	s_lshl_b32 s40, s7, 6
	s_lshl_b32 s50, s41, 5
	s_and_b32 s48, s6, 0x3ff80
	s_add_u32 s6, s2, s48
	v_add_u32_e32 v64, s40, v39
	s_addc_u32 s7, s3, 0
	v_add_u32_e32 v68, s40, v38
	v_add_u32_e32 v72, s40, v37
	v_add_u32_e32 v76, s40, v36
	v_add_u32_e32 v80, s40, v35
	v_add_u32_e32 v84, s40, v34
	v_add_u32_e32 v88, s40, v33
	v_add_u32_e32 v92, s40, v32
	v_add_u32_e32 v96, s40, v31
	v_add_u32_e32 v100, s40, v30
	v_add_u32_e32 v104, s40, v29
	v_add_u32_e32 v108, s40, v28
	v_add_u32_e32 v112, s40, v27
	v_add_u32_e32 v116, s40, v26
	v_ashrrev_i32_e32 v65, 31, v64
	v_mov_b64_e32 v[120:121], s[6:7]
	v_ashrrev_i32_e32 v69, 31, v68
	v_ashrrev_i32_e32 v73, 31, v72
	v_ashrrev_i32_e32 v77, 31, v76
	v_ashrrev_i32_e32 v81, 31, v80
	v_ashrrev_i32_e32 v85, 31, v84
	v_ashrrev_i32_e32 v89, 31, v88
	v_ashrrev_i32_e32 v93, 31, v92
	v_ashrrev_i32_e32 v97, 31, v96
	v_ashrrev_i32_e32 v101, 31, v100
	v_ashrrev_i32_e32 v105, 31, v104
	v_ashrrev_i32_e32 v109, 31, v108
	v_ashrrev_i32_e32 v113, 31, v112
	v_ashrrev_i32_e32 v117, 31, v116
	v_add_u32_e32 v122, s40, v1
	v_lshl_add_u64 v[62:63], v[64:65], 2, s[30:31]
	v_mad_i64_i32 v[64:65], s[6:7], v64, s18, v[120:121]
	v_lshl_add_u64 v[66:67], v[68:69], 2, s[30:31]
	v_mad_i64_i32 v[68:69], s[6:7], v68, s18, v[120:121]
	v_lshl_add_u64 v[70:71], v[72:73], 2, s[30:31]
	v_mad_i64_i32 v[72:73], s[6:7], v72, s18, v[120:121]
	v_lshl_add_u64 v[74:75], v[76:77], 2, s[30:31]
	v_mad_i64_i32 v[76:77], s[6:7], v76, s18, v[120:121]
	v_lshl_add_u64 v[78:79], v[80:81], 2, s[30:31]
	v_mad_i64_i32 v[80:81], s[6:7], v80, s18, v[120:121]
	v_lshl_add_u64 v[82:83], v[84:85], 2, s[30:31]
	v_mad_i64_i32 v[84:85], s[6:7], v84, s18, v[120:121]
	v_lshl_add_u64 v[86:87], v[88:89], 2, s[30:31]
	v_mad_i64_i32 v[88:89], s[6:7], v88, s18, v[120:121]
	v_lshl_add_u64 v[90:91], v[92:93], 2, s[30:31]
	v_mad_i64_i32 v[92:93], s[6:7], v92, s18, v[120:121]
	v_lshl_add_u64 v[94:95], v[96:97], 2, s[30:31]
	v_mad_i64_i32 v[96:97], s[6:7], v96, s18, v[120:121]
	v_lshl_add_u64 v[98:99], v[100:101], 2, s[30:31]
	v_mad_i64_i32 v[100:101], s[6:7], v100, s18, v[120:121]
	v_lshl_add_u64 v[102:103], v[104:105], 2, s[30:31]
	v_mad_i64_i32 v[104:105], s[6:7], v104, s18, v[120:121]
	v_lshl_add_u64 v[106:107], v[108:109], 2, s[30:31]
	v_mad_i64_i32 v[108:109], s[6:7], v108, s18, v[120:121]
	v_lshl_add_u64 v[110:111], v[112:113], 2, s[30:31]
	v_mad_i64_i32 v[112:113], s[6:7], v112, s18, v[120:121]
	v_lshl_add_u64 v[114:115], v[116:117], 2, s[30:31]
	v_mad_i64_i32 v[116:117], s[6:7], v116, s18, v[120:121]
	v_mad_i64_i32 v[120:121], s[6:7], v122, s18, v[120:121]
	s_mul_hi_u32 s6, s10, 0x1745d18
	v_ashrrev_i32_e32 v123, 31, v122
	s_lshl_b32 s10, s6, 8
	s_mul_i32 s6, s6, 0x160000
	v_lshl_add_u64 v[118:119], v[122:123], 2, s[30:31]
	v_lshl_add_u64 v[122:123], v[58:59], 0, s[10:11]
	s_or_b32 s10, s6, s48
	v_lshl_add_u64 v[124:125], v[60:61], 0, s[10:11]
	s_mov_b64 s[48:49], 0
	v_mov_b32_e32 v165, v164
	s_andn2_b64 vcc, exec, s[12:13]
	s_cbranch_vccnz .LBB0_721
	s_mov_b64 s[58:59], 0xb000
	v_lshl_add_u64 v[234:235], v[124:125], 0, v[2:3]
	v_mov_b32_e32 v236, v122
	v_mov_b32_e32 v237, v123
	global_load_dword v166, v[234:235], off nt
	v_lshl_add_u64 v[234:235], v[234:235], 0, s[58:59]
	global_load_dword v167, v[234:235], off nt
	v_lshl_add_u64 v[234:235], v[234:235], 0, s[58:59]
	global_load_dword v168, v[234:235], off nt
	v_lshl_add_u64 v[234:235], v[234:235], 0, s[58:59]
	global_load_dword v169, v[234:235], off nt
	v_lshl_add_u64 v[234:235], v[234:235], 0, s[58:59]
	global_load_dword v170, v[234:235], off nt
	v_lshl_add_u64 v[234:235], v[234:235], 0, s[58:59]
	global_load_dword v171, v[234:235], off nt
	v_lshl_add_u64 v[234:235], v[234:235], 0, s[58:59]
	global_load_dword v172, v[234:235], off nt
	v_lshl_add_u64 v[234:235], v[234:235], 0, s[58:59]
	global_load_dword v173, v[234:235], off nt
	v_lshl_add_u64 v[234:235], v[234:235], 0, s[58:59]
	global_load_dword v174, v[234:235], off nt
	v_lshl_add_u64 v[234:235], v[234:235], 0, s[58:59]
	global_load_dword v175, v[234:235], off nt
	v_lshl_add_u64 v[234:235], v[234:235], 0, s[58:59]
	global_load_dword v176, v[234:235], off nt
	v_lshl_add_u64 v[234:235], v[234:235], 0, s[58:59]
	global_load_dword v177, v[234:235], off nt
	v_lshl_add_u64 v[234:235], v[234:235], 0, s[58:59]
	global_load_dword v178, v[234:235], off nt
	v_lshl_add_u64 v[234:235], v[234:235], 0, s[58:59]
	global_load_dword v179, v[234:235], off nt
	v_lshl_add_u64 v[234:235], v[234:235], 0, s[58:59]
	global_load_dword v180, v[234:235], off nt
	v_lshl_add_u64 v[234:235], v[234:235], 0, s[58:59]
	global_load_dword v181, v[234:235], off nt
	v_lshl_add_u64 v[234:235], v[234:235], 0, s[58:59]
	global_load_dword v182, v[234:235], off nt
	v_lshl_add_u64 v[234:235], v[234:235], 0, s[58:59]
	global_load_dword v183, v[234:235], off nt
	v_lshl_add_u64 v[234:235], v[234:235], 0, s[58:59]
	global_load_dword v184, v[234:235], off nt
	v_lshl_add_u64 v[234:235], v[234:235], 0, s[58:59]
	global_load_dword v185, v[234:235], off nt
	v_lshl_add_u64 v[234:235], v[234:235], 0, s[58:59]
	global_load_dword v186, v[234:235], off nt
	v_lshl_add_u64 v[234:235], v[234:235], 0, s[58:59]
	global_load_dword v187, v[234:235], off nt
	v_lshl_add_u64 v[234:235], v[234:235], 0, s[58:59]
; template <bool GU>
; __device__ __forceinline__ void transpose_item(const float* W, int K, int N, bf16* WT, const float* gs, LAS float* scr, int item, int lane) {
;     ...
;     for (int i = 0; i < 32; ++i) { const int kk = 2 * i + (lane >> 5); float w = W[(size_t)(k0 + kk) * N + n0 + (lane & 31)]; if (gs) w *= gs[k0 + kk]; scr[kk * 33 + (lane & 31)] = w; }
	global_load_dword v188, v[234:235], off nt
	v_lshl_add_u64 v[234:235], v[234:235], 0, s[58:59]
	global_load_dword v189, v[234:235], off nt
	v_lshl_add_u64 v[234:235], v[234:235], 0, s[58:59]
	global_load_dword v190, v[234:235], off nt
	v_lshl_add_u64 v[234:235], v[234:235], 0, s[58:59]
	global_load_dword v191, v[234:235], off nt
	v_lshl_add_u64 v[234:235], v[234:235], 0, s[58:59]
	global_load_dword v192, v[234:235], off nt
	v_lshl_add_u64 v[234:235], v[234:235], 0, s[58:59]
	global_load_dword v193, v[234:235], off nt
	v_lshl_add_u64 v[234:235], v[234:235], 0, s[58:59]
	global_load_dword v194, v[234:235], off nt
	v_lshl_add_u64 v[234:235], v[234:235], 0, s[58:59]
	global_load_dword v195, v[234:235], off nt
	v_lshl_add_u64 v[234:235], v[234:235], 0, s[58:59]
	global_load_dword v199, v[234:235], off nt
	v_lshl_add_u64 v[234:235], v[234:235], 0, s[58:59]
	global_load_dword v200, v[234:235], off nt
	global_load_dword v201, v[236:237], off
	global_load_dword v202, v[236:237], off offset:8
	global_load_dword v203, v[236:237], off offset:16
	global_load_dword v204, v[236:237], off offset:24
	global_load_dword v205, v[236:237], off offset:32
	global_load_dword v206, v[236:237], off offset:40
	global_load_dword v207, v[236:237], off offset:48
	global_load_dword v208, v[236:237], off offset:56
	global_load_dword v209, v[236:237], off offset:64
	global_load_dword v210, v[236:237], off offset:72
	global_load_dword v211, v[236:237], off offset:80
	global_load_dword v212, v[236:237], off offset:88
	global_load_dword v213, v[236:237], off offset:96
	global_load_dword v214, v[236:237], off offset:104
	global_load_dword v215, v[236:237], off offset:112
	global_load_dword v216, v[236:237], off offset:120
	global_load_dword v217, v[236:237], off offset:128
	global_load_dword v218, v[236:237], off offset:136
	global_load_dword v219, v[236:237], off offset:144
	global_load_dword v220, v[236:237], off offset:152
	global_load_dword v221, v[236:237], off offset:160
	global_load_dword v222, v[236:237], off offset:168
	global_load_dword v223, v[236:237], off offset:176
	global_load_dword v224, v[236:237], off offset:184
	global_load_dword v225, v[236:237], off offset:192
	global_load_dword v226, v[236:237], off offset:200
	global_load_dword v227, v[236:237], off offset:208
	global_load_dword v228, v[236:237], off offset:216
	global_load_dword v229, v[236:237], off offset:224
	global_load_dword v230, v[236:237], off offset:232
	global_load_dword v231, v[236:237], off offset:240
	global_load_dword v232, v[236:237], off offset:248
	s_waitcnt vmcnt(31)
	v_mul_f32_e32 v166, v166, v201
	ds_write_b32 v165, v166
	s_waitcnt vmcnt(30)
	v_mul_f32_e32 v167, v167, v202
	ds_write_b32 v165, v167 offset:264
	s_waitcnt vmcnt(29)
	v_mul_f32_e32 v168, v168, v203
	ds_write_b32 v165, v168 offset:528
	s_waitcnt vmcnt(28)
	v_mul_f32_e32 v169, v169, v204
	ds_write_b32 v165, v169 offset:792
	s_waitcnt vmcnt(27)
	v_mul_f32_e32 v170, v170, v205
	ds_write_b32 v165, v170 offset:1056
	s_waitcnt vmcnt(26)
	v_mul_f32_e32 v171, v171, v206
	ds_write_b32 v165, v171 offset:1320
	s_waitcnt vmcnt(25)
	v_mul_f32_e32 v172, v172, v207
	ds_write_b32 v165, v172 offset:1584
	s_waitcnt vmcnt(24)
	v_mul_f32_e32 v173, v173, v208
	ds_write_b32 v165, v173 offset:1848
	s_waitcnt vmcnt(23)
	v_mul_f32_e32 v174, v174, v209
	ds_write_b32 v165, v174 offset:2112
	s_waitcnt vmcnt(22)
	v_mul_f32_e32 v175, v175, v210
	ds_write_b32 v165, v175 offset:2376
	s_waitcnt vmcnt(21)
	v_mul_f32_e32 v176, v176, v211
	ds_write_b32 v165, v176 offset:2640
	s_waitcnt vmcnt(20)
	v_mul_f32_e32 v177, v177, v212
	ds_write_b32 v165, v177 offset:2904
	s_waitcnt vmcnt(19)
	v_mul_f32_e32 v178, v178, v213
	ds_write_b32 v165, v178 offset:3168
	s_waitcnt vmcnt(18)
	v_mul_f32_e32 v179, v179, v214
	ds_write_b32 v165, v179 offset:3432
	s_waitcnt vmcnt(17)
	v_mul_f32_e32 v180, v180, v215
	ds_write_b32 v165, v180 offset:3696
	s_waitcnt vmcnt(16)
	v_mul_f32_e32 v181, v181, v216
	ds_write_b32 v165, v181 offset:3960
	s_waitcnt vmcnt(15)
	v_mul_f32_e32 v182, v182, v217
	ds_write_b32 v165, v182 offset:4224
	s_waitcnt vmcnt(14)
	v_mul_f32_e32 v183, v183, v218
	ds_write_b32 v165, v183 offset:4488
	s_waitcnt vmcnt(13)
	v_mul_f32_e32 v184, v184, v219
	ds_write_b32 v165, v184 offset:4752
	s_waitcnt vmcnt(12)
	v_mul_f32_e32 v185, v185, v220
	ds_write_b32 v165, v185 offset:5016
	s_waitcnt vmcnt(11)
	v_mul_f32_e32 v186, v186, v221
	ds_write_b32 v165, v186 offset:5280
	s_waitcnt vmcnt(10)
	v_mul_f32_e32 v187, v187, v222
	ds_write_b32 v165, v187 offset:5544
	s_waitcnt vmcnt(9)
	v_mul_f32_e32 v188, v188, v223
	ds_write_b32 v165, v188 offset:5808
	s_waitcnt vmcnt(8)
	v_mul_f32_e32 v189, v189, v224
	ds_write_b32 v165, v189 offset:6072
	s_waitcnt vmcnt(7)
	v_mul_f32_e32 v190, v190, v225
	ds_write_b32 v165, v190 offset:6336
	s_waitcnt vmcnt(6)
	v_mul_f32_e32 v191, v191, v226
	ds_write_b32 v165, v191 offset:6600
	s_waitcnt vmcnt(5)
	v_mul_f32_e32 v192, v192, v227
	ds_write_b32 v165, v192 offset:6864
	s_waitcnt vmcnt(4)
	v_mul_f32_e32 v193, v193, v228
	ds_write_b32 v165, v193 offset:7128
	s_waitcnt vmcnt(3)
	v_mul_f32_e32 v194, v194, v229
	ds_write_b32 v165, v194 offset:7392
	s_waitcnt vmcnt(2)
	v_mul_f32_e32 v195, v195, v230
	ds_write_b32 v165, v195 offset:7656
	s_waitcnt vmcnt(1)
	v_mul_f32_e32 v199, v199, v231
	ds_write_b32 v165, v199 offset:7920
	s_waitcnt vmcnt(0)
	v_mul_f32_e32 v200, v200, v232
	ds_write_b32 v165, v200 offset:8184
	s_branch .LBB0_753

; #define LAS __attribute__((address_space(3)))
; template <bool GU>
; __device__ __forceinline__ void transpose_item(const float* W, int K, int N, bf16* WT, const float* gs, LAS float* scr, int item, int lane) {
;     const int nblk = N / 32, kb = item / nblk, nb = item % nblk, k0 = 64 * kb, n0 = 32 * nb;
; #pragma unroll 16
;     for (int i = 0; i < 32; ++i) { const int kk = 2 * i + (lane >> 5); float w = W[(size_t)(k0 + kk) * N + n0 + (lane & 31)]; if (gs) w *= gs[k0 + kk]; scr[kk * 33 + (lane & 31)] = w; }
; __device__ __forceinline__ void conv_weights(LAS unsigned char* lds, unsigned char* ws, const PIn& I, const int l, const int wave, const int lane, const int gw, const int NGW, const int r_lo, const int r_hi) {
;     ...
;         if (r < I_IN) { transpose_item<false>(I.w_in + (size_t)l * DM * NIN, DM, NIN, (bf16*)(wb + W_IN), I.g_mix + l * DM, scr, r, lane); continue; } r -= I_IN;
.LBB0_758:
	s_mul_hi_i32 s6, s0, 0x38e38e39
	s_lshr_b32 s7, s6, 31
	s_ashr_i32 s6, s6, 4
	s_add_i32 s6, s6, s7
	s_mul_i32 s7, s6, 0x48
	s_sub_i32 s7, s0, s7
	s_lshl_b32 s48, s7, 5
	s_lshl_b32 s50, s6, 6
	s_ashr_i32 s49, s48, 31
	s_lshl_b64 s[6:7], s[48:49], 2
	s_ashr_i32 s51, s50, 31
	v_lshl_add_u64 v[66:67], v[56:57], 0, s[50:51]
	v_mov_b64_e32 v[68:69], s[6:7]
	v_lshl_add_u64 v[62:63], v[24:25], 0, s[6:7]
	v_mad_u64_u32 v[68:69], s[6:7], v66, s29, v[68:69]
	v_mad_i32_i24 v69, v67, s29, v69
	v_add_u32_e32 v70, s50, v56
	v_lshl_add_u64 v[64:65], v[66:67], 2, s[14:15]
	v_lshl_add_u64 v[66:67], v[24:25], 0, v[68:69]
	s_mov_b32 s10, 0
	v_mov_b32_e32 v71, v164
	s_andn2_b64 vcc, exec, s[16:17]
	s_cbranch_vccnz .LBB0_760
	s_mov_b64 s[58:59], 0x4800
	v_mov_b32_e32 v234, v66
	v_mov_b32_e32 v235, v67
	v_mov_b32_e32 v236, v64
	v_mov_b32_e32 v237, v65
	global_load_dword v166, v[234:235], off nt
	v_lshl_add_u64 v[234:235], v[234:235], 0, s[58:59]
	global_load_dword v167, v[234:235], off nt
	v_lshl_add_u64 v[234:235], v[234:235], 0, s[58:59]
	global_load_dword v168, v[234:235], off nt
	v_lshl_add_u64 v[234:235], v[234:235], 0, s[58:59]
	global_load_dword v169, v[234:235], off nt
	v_lshl_add_u64 v[234:235], v[234:235], 0, s[58:59]
	global_load_dword v170, v[234:235], off nt
	v_lshl_add_u64 v[234:235], v[234:235], 0, s[58:59]
	global_load_dword v171, v[234:235], off nt
	v_lshl_add_u64 v[234:235], v[234:235], 0, s[58:59]
	global_load_dword v172, v[234:235], off nt
	v_lshl_add_u64 v[234:235], v[234:235], 0, s[58:59]
	global_load_dword v173, v[234:235], off nt
	v_lshl_add_u64 v[234:235], v[234:235], 0, s[58:59]
	global_load_dword v174, v[234:235], off nt
	v_lshl_add_u64 v[234:235], v[234:235], 0, s[58:59]
	global_load_dword v175, v[234:235], off nt
	v_lshl_add_u64 v[234:235], v[234:235], 0, s[58:59]
	global_load_dword v176, v[234:235], off nt
	v_lshl_add_u64 v[234:235], v[234:235], 0, s[58:59]
	global_load_dword v177, v[234:235], off nt
	v_lshl_add_u64 v[234:235], v[234:235], 0, s[58:59]
	global_load_dword v178, v[234:235], off nt
	v_lshl_add_u64 v[234:235], v[234:235], 0, s[58:59]
	global_load_dword v179, v[234:235], off nt
	v_lshl_add_u64 v[234:235], v[234:235], 0, s[58:59]
	global_load_dword v180, v[234:235], off nt
	v_lshl_add_u64 v[234:235], v[234:235], 0, s[58:59]
	global_load_dword v181, v[234:235], off nt
	v_lshl_add_u64 v[234:235], v[234:235], 0, s[58:59]
	global_load_dword v182, v[234:235], off nt
	v_lshl_add_u64 v[234:235], v[234:235], 0, s[58:59]
	global_load_dword v183, v[234:235], off nt
	v_lshl_add_u64 v[234:235], v[234:235], 0, s[58:59]
	global_load_dword v184, v[234:235], off nt
	v_lshl_add_u64 v[234:235], v[234:235], 0, s[58:59]
	global_load_dword v185, v[234:235], off nt
	v_lshl_add_u64 v[234:235], v[234:235], 0, s[58:59]
	global_load_dword v186, v[234:235], off nt
	v_lshl_add_u64 v[234:235], v[234:235], 0, s[58:59]
	global_load_dword v187, v[234:235], off nt
	v_lshl_add_u64 v[234:235], v[234:235], 0, s[58:59]
	global_load_dword v188, v[234:235], off nt
	v_lshl_add_u64 v[234:235], v[234:235], 0, s[58:59]
	global_load_dword v189, v[234:235], off nt
	v_lshl_add_u64 v[234:235], v[234:235], 0, s[58:59]
	global_load_dword v190, v[234:235], off nt
	v_lshl_add_u64 v[234:235], v[234:235], 0, s[58:59]
	global_load_dword v191, v[234:235], off nt
	v_lshl_add_u64 v[234:235], v[234:235], 0, s[58:59]
	global_load_dword v192, v[234:235], off nt
	v_lshl_add_u64 v[234:235], v[234:235], 0, s[58:59]
	global_load_dword v193, v[234:235], off nt
	v_lshl_add_u64 v[234:235], v[234:235], 0, s[58:59]
	global_load_dword v194, v[234:235], off nt
	v_lshl_add_u64 v[234:235], v[234:235], 0, s[58:59]
	global_load_dword v195, v[234:235], off nt
	v_lshl_add_u64 v[234:235], v[234:235], 0, s[58:59]
	global_load_dword v199, v[234:235], off nt
	v_lshl_add_u64 v[234:235], v[234:235], 0, s[58:59]
	global_load_dword v200, v[234:235], off nt
	global_load_dword v201, v[236:237], off
	global_load_dword v202, v[236:237], off offset:8
	global_load_dword v203, v[236:237], off offset:16
	global_load_dword v204, v[236:237], off offset:24
	global_load_dword v205, v[236:237], off offset:32
	global_load_dword v206, v[236:237], off offset:40
	global_load_dword v207, v[236:237], off offset:48
	global_load_dword v208, v[236:237], off offset:56
	global_load_dword v209, v[236:237], off offset:64
	global_load_dword v210, v[236:237], off offset:72
	global_load_dword v211, v[236:237], off offset:80
	global_load_dword v212, v[236:237], off offset:88
	global_load_dword v213, v[236:237], off offset:96
	global_load_dword v214, v[236:237], off offset:104
	global_load_dword v215, v[236:237], off offset:112
	global_load_dword v216, v[236:237], off offset:120
	global_load_dword v217, v[236:237], off offset:128
	global_load_dword v218, v[236:237], off offset:136
	global_load_dword v219, v[236:237], off offset:144
	global_load_dword v220, v[236:237], off offset:152
	global_load_dword v221, v[236:237], off offset:160
	global_load_dword v222, v[236:237], off offset:168
	global_load_dword v223, v[236:237], off offset:176
	global_load_dword v224, v[236:237], off offset:184
	global_load_dword v225, v[236:237], off offset:192
	global_load_dword v226, v[236:237], off offset:200
	global_load_dword v227, v[236:237], off offset:208
	global_load_dword v228, v[236:237], off offset:216
	global_load_dword v229, v[236:237], off offset:224
	global_load_dword v230, v[236:237], off offset:232
	global_load_dword v231, v[236:237], off offset:240
	global_load_dword v232, v[236:237], off offset:248
	s_waitcnt vmcnt(31)
; template <bool GU>
; __device__ __forceinline__ void transpose_item(const float* W, int K, int N, bf16* WT, const float* gs, LAS float* scr, int item, int lane) {
;     ...
;     for (int i = 0; i < 32; ++i) { const int kk = 2 * i + (lane >> 5); float w = W[(size_t)(k0 + kk) * N + n0 + (lane & 31)]; if (gs) w *= gs[k0 + kk]; scr[kk * 33 + (lane & 31)] = w; }
	v_mul_f32_e32 v166, v166, v201
	ds_write_b32 v71, v166
	s_waitcnt vmcnt(30)
	v_mul_f32_e32 v167, v167, v202
	ds_write_b32 v71, v167 offset:264
	s_waitcnt vmcnt(29)
	v_mul_f32_e32 v168, v168, v203
	ds_write_b32 v71, v168 offset:528
	s_waitcnt vmcnt(28)
	v_mul_f32_e32 v169, v169, v204
	ds_write_b32 v71, v169 offset:792
	s_waitcnt vmcnt(27)
	v_mul_f32_e32 v170, v170, v205
	ds_write_b32 v71, v170 offset:1056
	s_waitcnt vmcnt(26)
	v_mul_f32_e32 v171, v171, v206
	ds_write_b32 v71, v171 offset:1320
	s_waitcnt vmcnt(25)
	v_mul_f32_e32 v172, v172, v207
	ds_write_b32 v71, v172 offset:1584
	s_waitcnt vmcnt(24)
	v_mul_f32_e32 v173, v173, v208
	ds_write_b32 v71, v173 offset:1848
	s_waitcnt vmcnt(23)
	v_mul_f32_e32 v174, v174, v209
	ds_write_b32 v71, v174 offset:2112
	s_waitcnt vmcnt(22)
	v_mul_f32_e32 v175, v175, v210
	ds_write_b32 v71, v175 offset:2376
	s_waitcnt vmcnt(21)
	v_mul_f32_e32 v176, v176, v211
	ds_write_b32 v71, v176 offset:2640
	s_waitcnt vmcnt(20)
	v_mul_f32_e32 v177, v177, v212
	ds_write_b32 v71, v177 offset:2904
	s_waitcnt vmcnt(19)
	v_mul_f32_e32 v178, v178, v213
	ds_write_b32 v71, v178 offset:3168
	s_waitcnt vmcnt(18)
	v_mul_f32_e32 v179, v179, v214
	ds_write_b32 v71, v179 offset:3432
	s_waitcnt vmcnt(17)
	v_mul_f32_e32 v180, v180, v215
	ds_write_b32 v71, v180 offset:3696
	s_waitcnt vmcnt(16)
	v_mul_f32_e32 v181, v181, v216
	ds_write_b32 v71, v181 offset:3960
	s_waitcnt vmcnt(15)
	v_mul_f32_e32 v182, v182, v217
	ds_write_b32 v71, v182 offset:4224
	s_waitcnt vmcnt(14)
	v_mul_f32_e32 v183, v183, v218
	ds_write_b32 v71, v183 offset:4488
	s_waitcnt vmcnt(13)
	v_mul_f32_e32 v184, v184, v219
	ds_write_b32 v71, v184 offset:4752
	s_waitcnt vmcnt(12)
	v_mul_f32_e32 v185, v185, v220
	ds_write_b32 v71, v185 offset:5016
	s_waitcnt vmcnt(11)
	v_mul_f32_e32 v186, v186, v221
	ds_write_b32 v71, v186 offset:5280
	s_waitcnt vmcnt(10)
	v_mul_f32_e32 v187, v187, v222
	ds_write_b32 v71, v187 offset:5544
	s_waitcnt vmcnt(9)
	v_mul_f32_e32 v188, v188, v223
	ds_write_b32 v71, v188 offset:5808
	s_waitcnt vmcnt(8)
	v_mul_f32_e32 v189, v189, v224
	ds_write_b32 v71, v189 offset:6072
	s_waitcnt vmcnt(7)
	v_mul_f32_e32 v190, v190, v225
	ds_write_b32 v71, v190 offset:6336
	s_waitcnt vmcnt(6)
	v_mul_f32_e32 v191, v191, v226
	ds_write_b32 v71, v191 offset:6600
	s_waitcnt vmcnt(5)
	v_mul_f32_e32 v192, v192, v227
	ds_write_b32 v71, v192 offset:6864
	s_waitcnt vmcnt(4)
	v_mul_f32_e32 v193, v193, v228
	ds_write_b32 v71, v193 offset:7128
	s_waitcnt vmcnt(3)
	v_mul_f32_e32 v194, v194, v229
	ds_write_b32 v71, v194 offset:7392
	s_waitcnt vmcnt(2)
	v_mul_f32_e32 v195, v195, v230
	ds_write_b32 v71, v195 offset:7656
	s_waitcnt vmcnt(1)
	v_mul_f32_e32 v199, v199, v231
	ds_write_b32 v71, v199 offset:7920
	s_waitcnt vmcnt(0)
	v_mul_f32_e32 v200, v200, v232
	ds_write_b32 v71, v200 offset:8184
	s_branch .LBB0_703

; __device__ __forceinline__ unsigned cvt_pk(float lo, float hi) { unsigned r; asm("v_cvt_pk_bf16_f32 %0, %1, %2" : "=v"(r) : "v"(lo), "v"(hi)); return r; }
;     ...
;     for (size_t i = gtid * 8; i < NA; i += gth * 8) {
;         const size_t gi = (size_t)l * NA + i;
;         const f32x4 a = *(const f32x4*)(I.cak + gi), b = *(const f32x4*)(I.cak + gi + 4), c = *(const f32x4*)(I.cav + gi), d = *(const f32x4*)(I.cav + gi + 4);
;         v4u w; w.x = cvt_pk(a[0], a[1]); w.y = cvt_pk(a[2], a[3]); w.z = cvt_pk(b[0], b[1]); w.w = cvt_pk(b[2], b[3]);
;         *(v4u*)((bf16*)(ws + WS_CKA) + gi) = w;
;         w.x = cvt_pk(c[0], c[1]); w.y = cvt_pk(c[2], c[3]); w.z = cvt_pk(d[0], d[1]); w.w = cvt_pk(d[2], d[3]);
;         *(v4u*)((bf16*)(ws + WS_CVA) + gi) = w;
;         if (((i >> 9) & 511) >= 64) { float* dk = out + O_AKS + gi - 32768; float* dv = out + O_AVS + gi - 32768;
;             *(f32x4*)dk = a; *(f32x4*)(dk + 4) = b; *(f32x4*)dv = c; *(f32x4*)(dv + 4) = d; }
;     }
.LBB0_857:
	v_lshl_add_u64 v[0:1], s[20:21], 0, v[18:19]
	v_lshl_add_u64 v[4:5], v[0:1], 0, s[16:17]
	v_add_co_u32_e32 v0, vcc, 0x1000000, v0
	v_lshl_add_u64 v[12:13], s[22:23], 0, v[18:19]
	s_nop 0
	v_addc_co_u32_e32 v1, vcc, 0, v1, vcc
	v_add_co_u32_e32 v8, vcc, s2, v12
	global_load_dwordx4 v[0:3], v[0:1], off nt
	s_nop 0
	global_load_dwordx4 v[4:7], v[4:5], off offset:16
	v_addc_co_u32_e32 v9, vcc, 0, v13, vcc
	v_lshl_add_u64 v[12:13], v[12:13], 0, s[16:17]
	global_load_dwordx4 v[8:11], v[8:9], off
	v_add_co_u32_e32 v32, vcc, s3, v22
	global_load_dwordx4 v[12:15], v[12:13], off offset:16
	v_and_b32_e32 v24, 0x38000, v26
	v_addc_co_u32_e32 v33, vcc, -1, v23, vcc
	v_cmp_ne_u64_e32 vcc, 0, v[24:25]
	s_waitcnt vmcnt(3)
	v_cvt_pk_bf16_f32 v28, v0, v1
	v_cvt_pk_bf16_f32 v29, v2, v3
	s_waitcnt vmcnt(2)
	v_cvt_pk_bf16_f32 v30, v4, v5
	v_cvt_pk_bf16_f32 v31, v6, v7
	global_store_dwordx4 v[32:33], v[28:31], off
	s_waitcnt vmcnt(2)
	s_nop 0
	v_cvt_pk_bf16_f32 v28, v8, v9
	v_cvt_pk_bf16_f32 v29, v10, v11
	s_waitcnt vmcnt(1)
	v_cvt_pk_bf16_f32 v30, v12, v13
	v_cvt_pk_bf16_f32 v31, v14, v15
	global_store_dwordx4 v[22:23], v[28:31], off
	s_and_saveexec_b64 s[38:39], vcc
	s_cbranch_execz .LBB0_856
	v_lshl_add_u64 v[28:29], s[36:37], 0, v[18:19]
	v_add_co_u32_e32 v30, vcc, 0x9c60000, v28
	s_nop 1
	v_addc_co_u32_e32 v31, vcc, 0, v29, vcc
	global_store_dwordx4 v[30:31], v[0:3], off
	global_store_dwordx4 v[30:31], v[4:7], off offset:16
	s_nop 0
	v_add_co_u32_e32 v0, vcc, 0xbc60000, v28
	s_nop 1
	v_addc_co_u32_e32 v1, vcc, 0, v29, vcc
	global_store_dwordx4 v[0:1], v[8:11], off
	global_store_dwordx4 v[0:1], v[12:15], off offset:16
	s_branch .LBB0_856

; __device__ __forceinline__ unsigned cvt_pk(float lo, float hi) { unsigned r; asm("v_cvt_pk_bf16_f32 %0, %1, %2" : "=v"(r) : "v"(lo), "v"(hi)); return r; }
;     ...
;     for (size_t i = gtid * 8; i < NB; i += gth * 8) {
;         const size_t gi = (size_t)l * NB + i;
;         const f32x4 a = *(const f32x4*)(I.cbk + gi), b = *(const f32x4*)(I.cbk + gi + 4), c = *(const f32x4*)(I.cbv + gi), d = *(const f32x4*)(I.cbv + gi + 4);
;         v4u w; w.x = cvt_pk(a[0], a[1]); w.y = cvt_pk(a[2], a[3]); w.z = cvt_pk(b[0], b[1]); w.w = cvt_pk(b[2], b[3]);
;         *(v4u*)((bf16*)(ws + WS_CKB) + gi) = w;
;         w.x = cvt_pk(c[0], c[1]); w.y = cvt_pk(c[2], c[3]); w.z = cvt_pk(d[0], d[1]); w.w = cvt_pk(d[2], d[3]);
;         *(v4u*)((bf16*)(ws + WS_CVB) + gi) = w;
;         if (((i >> 7) & 127) >= 64) { float* dk = out + O_BKS + gi - 8192; float* dv = out + O_BVS + gi - 8192;
;             *(f32x4*)dk = a; *(f32x4*)(dk + 4) = b; *(f32x4*)dv = c; *(f32x4*)(dv + 4) = d; }
;     }
.LBB0_862:
	v_lshl_add_u64 v[0:1], s[24:25], 0, v[18:19]
	v_lshl_add_u64 v[4:5], v[0:1], 0, s[14:15]
	v_add_co_u32_e32 v0, vcc, 0x100000, v0
	v_lshl_add_u64 v[12:13], s[26:27], 0, v[18:19]
	s_nop 0
	v_addc_co_u32_e32 v1, vcc, 0, v1, vcc
	v_add_co_u32_e32 v8, vcc, s2, v12
	global_load_dwordx4 v[0:3], v[0:1], off nt
	s_nop 0
	global_load_dwordx4 v[4:7], v[4:5], off offset:16
	v_addc_co_u32_e32 v9, vcc, 0, v13, vcc
	v_lshl_add_u64 v[12:13], v[12:13], 0, s[14:15]
	global_load_dwordx4 v[8:11], v[8:9], off
	v_add_co_u32_e32 v26, vcc, s3, v20
	global_load_dwordx4 v[12:15], v[12:13], off offset:16
	v_and_b32_e32 v28, 0x2000, v16
	v_addc_co_u32_e32 v27, vcc, -1, v21, vcc
	v_cmp_ne_u32_e32 vcc, 0, v28
	s_waitcnt vmcnt(3)
	v_cvt_pk_bf16_f32 v22, v0, v1
	v_cvt_pk_bf16_f32 v23, v2, v3
	s_waitcnt vmcnt(2)
	v_cvt_pk_bf16_f32 v24, v4, v5
	v_cvt_pk_bf16_f32 v25, v6, v7
	global_store_dwordx4 v[26:27], v[22:25], off
	s_waitcnt vmcnt(2)
	s_nop 0
	v_cvt_pk_bf16_f32 v22, v8, v9
	v_cvt_pk_bf16_f32 v23, v10, v11
	s_waitcnt vmcnt(1)
	v_cvt_pk_bf16_f32 v24, v12, v13
	v_cvt_pk_bf16_f32 v25, v14, v15
	global_store_dwordx4 v[20:21], v[22:25], off
	s_and_saveexec_b64 s[20:21], vcc
	s_cbranch_execz .LBB0_861
	v_lshl_add_u64 v[22:23], s[46:47], 0, v[18:19]
	v_add_co_u32_e32 v24, vcc, 0xcd78000, v22
	s_nop 1
	v_addc_co_u32_e32 v25, vcc, 0, v23, vcc
	global_store_dwordx4 v[24:25], v[0:3], off
	global_store_dwordx4 v[24:25], v[4:7], off offset:16
	s_nop 0
	v_add_co_u32_e32 v0, vcc, 0xcf78000, v22
	s_nop 1
	v_addc_co_u32_e32 v1, vcc, 0, v23, vcc
	global_store_dwordx4 v[0:1], v[8:11], off
	global_store_dwordx4 v[0:1], v[12:15], off offset:16
	s_branch .LBB0_861
